# GEMM1 gate epilogue regenerated: all VALU, then 16 even-quad half-line stores, then 16 odd-quad stores (same layout); + no entry grid.sync
# speedup vs baseline: 1.0113x; 1.0113x over previous
; __device__ __forceinline__ float sigm(float v) { return __builtin_amdgcn_rcpf(1.0f + __builtin_amdgcn_exp2f(-LOG2E * v)); }
; __device__ __forceinline__ unsigned cvt_pk_bf16(float lo, float hi) { f32x2_t v = {lo, hi}; bf16x2_t b = __builtin_convertvector(v, bf16x2_t); return __builtin_bit_cast(unsigned, b); }
; #define EPI_FENCE() asm volatile("" ::: "memory")
; #define EPI_LANE() int t__ = threadIdx.x; asm volatile("" : "+v"(t__)); const int wid__ = __builtin_amdgcn_readfirstlane(t__ >> 6); wr = wid__ >> 2; wc = wid__ & 3; fr = t__ & 15; fq = (t__ & 63) >> 4
; template <int MODE> __device__ __forceinline__ float actf(float v) {
;     if (MODE == 1) return v * sigm(v);
;     if (MODE == 2) return fminf(1.0f + __builtin_amdgcn_exp2f(-LOG2E * v), 1e30f);
;     if (MODE == 3) return v * QSCALE;
;     return v;
; }
;     template <int MODE> __device__ __forceinline__ void run(const f32x4 (&acc)[2][2][4][2], const Unit& u, int wr, int wc, int fr, int fq) const {
;         EPI_LANE();
;         const int pn = u.pn, colt = pn * BM, t = colt >> 9;
;         char* base = (MODE == 2) ? (char*)(O + (size_t)6 * ((size_t)MTOK * 512)) + ((size_t)(((pn - 12) * 128 + u.pm) * 8 + wid__)) * 16384
;                                  : (char*)(O + (size_t)t * ((size_t)MTOK * 512) + (size_t)u.pm * BM * 512 + (colt & 511));
;         unsigned off0 = (MODE == 2) ? (unsigned)((t__ & 63) * 16) : (unsigned)((wr * 64 + fr) * 512 + wc * 32 + 8 * fq) * 2u; asm volatile("" : "+v"(off0));
; #pragma unroll
;         for (int bj = 0; bj < 2; ++bj) {
; #pragma unroll
;             for (int ai = 0; ai < 2; ++ai)
; #pragma unroll
;                 for (int m = 0; m < 4; ++m) { const unsigned off = off0 + ((MODE == 2) ? (unsigned)(((ai * 4 + m) * 2 + bj) * 1024) : (unsigned)((ai * HALF + m * 16) * 512 + bj * HALF) * 2u);
;                     const f32x4 v0 = acc[ai][bj][m][0], v1 = acc[ai][bj][m][1];
;                     u32x4 w; w.x = cvt_pk_bf16(actf<MODE>(v0[0]), actf<MODE>(v0[1])); w.y = cvt_pk_bf16(actf<MODE>(v0[2]), actf<MODE>(v0[3]));
;                     w.z = cvt_pk_bf16(actf<MODE>(v1[0]), actf<MODE>(v1[1])); w.w = cvt_pk_bf16(actf<MODE>(v1[2]), actf<MODE>(v1[3]));
;                     *(u32x4*)(base + off) = w; }
;             EPI_FENCE();
;         }
.LBB0_403:
	v_mov_b32_e32 v142, v212
	s_lshl_b32 s60, s72, 7
	s_add_i32 s60, s60, s54
	v_readfirstlane_b32 s55, v142
	s_lshl_b32 s54, s60, 3
	s_ashr_i32 s55, s55, 6
	s_add_i32 s54, s54, s55
	s_addk_i32 s54, 0xd000
	s_ashr_i32 s55, s54, 31
	s_lshl_b64 s[54:55], s[54:55], 14
	v_lshlrev_b32_e32 v142, 4, v142
	s_add_u32 s54, s33, s54
	s_addc_u32 s55, s37, s55
	v_and_b32_e32 v142, 0x3f0, v142
	v_add_u32_e32 v144, 0x400, v142
	v_add_u32_e32 v145, 0x800, v142
	v_add_u32_e32 v146, 0xc00, v142
	v_add_u32_e32 v147, 0x1000, v142
	v_add_u32_e32 v148, 0x1400, v142
	v_add_u32_e32 v149, 0x1800, v142
	v_add_u32_e32 v150, 0x1c00, v142
	v_add_u32_e32 v151, 0x2000, v142
	v_add_u32_e32 v152, 0x2400, v142
	v_add_u32_e32 v153, 0x2800, v142
	v_add_u32_e32 v154, 0x2c00, v142
	v_add_u32_e32 v155, 0x3000, v142
	v_add_u32_e32 v156, 0x3400, v142
	v_add_u32_e32 v157, 0x3800, v142
	v_add_u32_e32 v158, 0x3c00, v142
	v_mul_f32_e32 v126, 0xbfb8aa3b, v126
	v_mul_f32_e32 v127, 0xbfb8aa3b, v127
	v_mul_f32_e32 v128, 0xbfb8aa3b, v128
	v_mul_f32_e32 v129, 0xbfb8aa3b, v129
	v_mul_f32_e32 v122, 0xbfb8aa3b, v122
	v_mul_f32_e32 v123, 0xbfb8aa3b, v123
	v_mul_f32_e32 v124, 0xbfb8aa3b, v124
	v_mul_f32_e32 v125, 0xbfb8aa3b, v125
	v_exp_f32_e32 v126, v126
	v_exp_f32_e32 v127, v127
	v_exp_f32_e32 v128, v128
	v_exp_f32_e32 v129, v129
	v_exp_f32_e32 v122, v122
	v_exp_f32_e32 v123, v123
	v_exp_f32_e32 v124, v124
	v_exp_f32_e32 v125, v125
	v_add_f32_e32 v126, 1.0, v126
	v_add_f32_e32 v127, 1.0, v127
	v_add_f32_e32 v128, 1.0, v128
	v_add_f32_e32 v129, 1.0, v129
	v_add_f32_e32 v122, 1.0, v122
	v_add_f32_e32 v123, 1.0, v123
	v_add_f32_e32 v124, 1.0, v124
	v_add_f32_e32 v125, 1.0, v125
	v_min_f32_e32 v126, 0x7149f2ca, v126
	v_min_f32_e32 v127, 0x7149f2ca, v127
	v_min_f32_e32 v128, 0x7149f2ca, v128
	v_min_f32_e32 v129, 0x7149f2ca, v129
	v_min_f32_e32 v122, 0x7149f2ca, v122
	v_min_f32_e32 v123, 0x7149f2ca, v123
	v_min_f32_e32 v124, 0x7149f2ca, v124
	v_min_f32_e32 v125, 0x7149f2ca, v125
	v_cvt_pk_bf16_f32 v126, v126, v127
	v_cvt_pk_bf16_f32 v127, v128, v129
	v_cvt_pk_bf16_f32 v128, v122, v123
	v_cvt_pk_bf16_f32 v129, v124, v125
	v_mul_f32_e32 v68, 0xbfb8aa3b, v68
	v_mul_f32_e32 v69, 0xbfb8aa3b, v69
	v_mul_f32_e32 v70, 0xbfb8aa3b, v70
	v_mul_f32_e32 v71, 0xbfb8aa3b, v71
	v_mul_f32_e32 v64, 0xbfb8aa3b, v64
	v_mul_f32_e32 v65, 0xbfb8aa3b, v65
	v_mul_f32_e32 v66, 0xbfb8aa3b, v66
	v_mul_f32_e32 v67, 0xbfb8aa3b, v67
	v_exp_f32_e32 v68, v68
	v_exp_f32_e32 v69, v69
	v_exp_f32_e32 v70, v70
	v_exp_f32_e32 v71, v71
	v_exp_f32_e32 v64, v64
	v_exp_f32_e32 v65, v65
	v_exp_f32_e32 v66, v66
	v_exp_f32_e32 v67, v67
	v_add_f32_e32 v68, 1.0, v68
	v_add_f32_e32 v69, 1.0, v69
	v_add_f32_e32 v70, 1.0, v70
	v_add_f32_e32 v71, 1.0, v71
	v_add_f32_e32 v64, 1.0, v64
	v_add_f32_e32 v65, 1.0, v65
	v_add_f32_e32 v66, 1.0, v66
	v_add_f32_e32 v67, 1.0, v67
	v_min_f32_e32 v68, 0x7149f2ca, v68
	v_min_f32_e32 v69, 0x7149f2ca, v69
	v_min_f32_e32 v70, 0x7149f2ca, v70
	v_min_f32_e32 v71, 0x7149f2ca, v71
	v_min_f32_e32 v64, 0x7149f2ca, v64
	v_min_f32_e32 v65, 0x7149f2ca, v65
	v_min_f32_e32 v66, 0x7149f2ca, v66
	v_min_f32_e32 v67, 0x7149f2ca, v67
	v_cvt_pk_bf16_f32 v68, v68, v69
	v_cvt_pk_bf16_f32 v69, v70, v71
	v_cvt_pk_bf16_f32 v70, v64, v65
	v_cvt_pk_bf16_f32 v71, v66, v67
	v_mul_f32_e32 v118, 0xbfb8aa3b, v118
	v_mul_f32_e32 v119, 0xbfb8aa3b, v119
	v_mul_f32_e32 v120, 0xbfb8aa3b, v120
	v_mul_f32_e32 v121, 0xbfb8aa3b, v121
	v_mul_f32_e32 v114, 0xbfb8aa3b, v114
	v_mul_f32_e32 v115, 0xbfb8aa3b, v115
	v_mul_f32_e32 v116, 0xbfb8aa3b, v116
	v_mul_f32_e32 v117, 0xbfb8aa3b, v117
	v_exp_f32_e32 v118, v118
	v_exp_f32_e32 v119, v119
	v_exp_f32_e32 v120, v120
	v_exp_f32_e32 v121, v121
	v_exp_f32_e32 v114, v114
	v_exp_f32_e32 v115, v115
	v_exp_f32_e32 v116, v116
	v_exp_f32_e32 v117, v117
	v_add_f32_e32 v118, 1.0, v118
	v_add_f32_e32 v119, 1.0, v119
	v_add_f32_e32 v120, 1.0, v120
	v_add_f32_e32 v121, 1.0, v121
	v_add_f32_e32 v114, 1.0, v114
	v_add_f32_e32 v115, 1.0, v115
	v_add_f32_e32 v116, 1.0, v116
	v_add_f32_e32 v117, 1.0, v117
	v_min_f32_e32 v118, 0x7149f2ca, v118
	v_min_f32_e32 v119, 0x7149f2ca, v119
	v_min_f32_e32 v120, 0x7149f2ca, v120
	v_min_f32_e32 v121, 0x7149f2ca, v121
	v_min_f32_e32 v114, 0x7149f2ca, v114
	v_min_f32_e32 v115, 0x7149f2ca, v115
	v_min_f32_e32 v116, 0x7149f2ca, v116
	v_min_f32_e32 v117, 0x7149f2ca, v117
	v_cvt_pk_bf16_f32 v118, v118, v119
	v_cvt_pk_bf16_f32 v119, v120, v121
	v_cvt_pk_bf16_f32 v120, v114, v115
	v_cvt_pk_bf16_f32 v121, v116, v117
	v_mul_f32_e32 v60, 0xbfb8aa3b, v60
	v_mul_f32_e32 v61, 0xbfb8aa3b, v61
	v_mul_f32_e32 v62, 0xbfb8aa3b, v62
	v_mul_f32_e32 v63, 0xbfb8aa3b, v63
	v_mul_f32_e32 v56, 0xbfb8aa3b, v56
	v_mul_f32_e32 v57, 0xbfb8aa3b, v57
	v_mul_f32_e32 v58, 0xbfb8aa3b, v58
	v_mul_f32_e32 v59, 0xbfb8aa3b, v59
	v_exp_f32_e32 v60, v60
	v_exp_f32_e32 v61, v61
	v_exp_f32_e32 v62, v62
	v_exp_f32_e32 v63, v63
	v_exp_f32_e32 v56, v56
	v_exp_f32_e32 v57, v57
	v_exp_f32_e32 v58, v58
	v_exp_f32_e32 v59, v59
	v_add_f32_e32 v60, 1.0, v60
	v_add_f32_e32 v61, 1.0, v61
	v_add_f32_e32 v62, 1.0, v62
	v_add_f32_e32 v63, 1.0, v63
	v_add_f32_e32 v56, 1.0, v56
	v_add_f32_e32 v57, 1.0, v57
	v_add_f32_e32 v58, 1.0, v58
	v_add_f32_e32 v59, 1.0, v59
	v_min_f32_e32 v60, 0x7149f2ca, v60
	v_min_f32_e32 v61, 0x7149f2ca, v61
	v_min_f32_e32 v62, 0x7149f2ca, v62
	v_min_f32_e32 v63, 0x7149f2ca, v63
	v_min_f32_e32 v56, 0x7149f2ca, v56
	v_min_f32_e32 v57, 0x7149f2ca, v57
	v_min_f32_e32 v58, 0x7149f2ca, v58
	v_min_f32_e32 v59, 0x7149f2ca, v59
	v_cvt_pk_bf16_f32 v60, v60, v61
	v_cvt_pk_bf16_f32 v61, v62, v63
	v_cvt_pk_bf16_f32 v62, v56, v57
	v_cvt_pk_bf16_f32 v63, v58, v59
	v_mul_f32_e32 v110, 0xbfb8aa3b, v110
	v_mul_f32_e32 v111, 0xbfb8aa3b, v111
; __device__ __forceinline__ float sigm(float v) { return __builtin_amdgcn_rcpf(1.0f + __builtin_amdgcn_exp2f(-LOG2E * v)); }
; __device__ __forceinline__ unsigned cvt_pk_bf16(float lo, float hi) { f32x2_t v = {lo, hi}; bf16x2_t b = __builtin_convertvector(v, bf16x2_t); return __builtin_bit_cast(unsigned, b); }
; #define EPI_FENCE() asm volatile("" ::: "memory")
; #define EPI_LANE() int t__ = threadIdx.x; asm volatile("" : "+v"(t__)); const int wid__ = __builtin_amdgcn_readfirstlane(t__ >> 6); wr = wid__ >> 2; wc = wid__ & 3; fr = t__ & 15; fq = (t__ & 63) >> 4
; template <int MODE> __device__ __forceinline__ float actf(float v) {
;     if (MODE == 1) return v * sigm(v);
;     if (MODE == 2) return fminf(1.0f + __builtin_amdgcn_exp2f(-LOG2E * v), 1e30f);
;     if (MODE == 3) return v * QSCALE;
;     return v;
; }
;     template <int MODE> __device__ __forceinline__ void run(const f32x4 (&acc)[2][2][4][2], const Unit& u, int wr, int wc, int fr, int fq) const {
;         EPI_LANE();
;         const int pn = u.pn, colt = pn * BM, t = colt >> 9;
;         char* base = (MODE == 2) ? (char*)(O + (size_t)6 * ((size_t)MTOK * 512)) + ((size_t)(((pn - 12) * 128 + u.pm) * 8 + wid__)) * 16384
;                                  : (char*)(O + (size_t)t * ((size_t)MTOK * 512) + (size_t)u.pm * BM * 512 + (colt & 511));
;         unsigned off0 = (MODE == 2) ? (unsigned)((t__ & 63) * 16) : (unsigned)((wr * 64 + fr) * 512 + wc * 32 + 8 * fq) * 2u; asm volatile("" : "+v"(off0));
; #pragma unroll
;         for (int bj = 0; bj < 2; ++bj) {
; #pragma unroll
;             for (int ai = 0; ai < 2; ++ai)
; #pragma unroll
;                 for (int m = 0; m < 4; ++m) { const unsigned off = off0 + ((MODE == 2) ? (unsigned)(((ai * 4 + m) * 2 + bj) * 1024) : (unsigned)((ai * HALF + m * 16) * 512 + bj * HALF) * 2u);
;                     const f32x4 v0 = acc[ai][bj][m][0], v1 = acc[ai][bj][m][1];
;                     u32x4 w; w.x = cvt_pk_bf16(actf<MODE>(v0[0]), actf<MODE>(v0[1])); w.y = cvt_pk_bf16(actf<MODE>(v0[2]), actf<MODE>(v0[3]));
;                     w.z = cvt_pk_bf16(actf<MODE>(v1[0]), actf<MODE>(v1[1])); w.w = cvt_pk_bf16(actf<MODE>(v1[2]), actf<MODE>(v1[3]));
;                     *(u32x4*)(base + off) = w; }
;             EPI_FENCE();
;         }
	v_mul_f32_e32 v112, 0xbfb8aa3b, v112
	v_mul_f32_e32 v113, 0xbfb8aa3b, v113
	v_mul_f32_e32 v106, 0xbfb8aa3b, v106
	v_mul_f32_e32 v107, 0xbfb8aa3b, v107
	v_mul_f32_e32 v108, 0xbfb8aa3b, v108
	v_mul_f32_e32 v109, 0xbfb8aa3b, v109
	v_exp_f32_e32 v110, v110
	v_exp_f32_e32 v111, v111
	v_exp_f32_e32 v112, v112
	v_exp_f32_e32 v113, v113
	v_exp_f32_e32 v106, v106
	v_exp_f32_e32 v107, v107
	v_exp_f32_e32 v108, v108
	v_exp_f32_e32 v109, v109
	v_add_f32_e32 v110, 1.0, v110
	v_add_f32_e32 v111, 1.0, v111
	v_add_f32_e32 v112, 1.0, v112
	v_add_f32_e32 v113, 1.0, v113
	v_add_f32_e32 v106, 1.0, v106
	v_add_f32_e32 v107, 1.0, v107
	v_add_f32_e32 v108, 1.0, v108
	v_add_f32_e32 v109, 1.0, v109
	v_min_f32_e32 v110, 0x7149f2ca, v110
	v_min_f32_e32 v111, 0x7149f2ca, v111
	v_min_f32_e32 v112, 0x7149f2ca, v112
	v_min_f32_e32 v113, 0x7149f2ca, v113
	v_min_f32_e32 v106, 0x7149f2ca, v106
	v_min_f32_e32 v107, 0x7149f2ca, v107
	v_min_f32_e32 v108, 0x7149f2ca, v108
	v_min_f32_e32 v109, 0x7149f2ca, v109
	v_cvt_pk_bf16_f32 v110, v110, v111
	v_cvt_pk_bf16_f32 v111, v112, v113
	v_cvt_pk_bf16_f32 v112, v106, v107
	v_cvt_pk_bf16_f32 v113, v108, v109
	v_mul_f32_e32 v52, 0xbfb8aa3b, v52
	v_mul_f32_e32 v53, 0xbfb8aa3b, v53
	v_mul_f32_e32 v54, 0xbfb8aa3b, v54
	v_mul_f32_e32 v55, 0xbfb8aa3b, v55
	v_mul_f32_e32 v48, 0xbfb8aa3b, v48
	v_mul_f32_e32 v49, 0xbfb8aa3b, v49
	v_mul_f32_e32 v50, 0xbfb8aa3b, v50
	v_mul_f32_e32 v51, 0xbfb8aa3b, v51
	v_exp_f32_e32 v52, v52
	v_exp_f32_e32 v53, v53
	v_exp_f32_e32 v54, v54
	v_exp_f32_e32 v55, v55
	v_exp_f32_e32 v48, v48
	v_exp_f32_e32 v49, v49
	v_exp_f32_e32 v50, v50
	v_exp_f32_e32 v51, v51
	v_add_f32_e32 v52, 1.0, v52
	v_add_f32_e32 v53, 1.0, v53
	v_add_f32_e32 v54, 1.0, v54
	v_add_f32_e32 v55, 1.0, v55
	v_add_f32_e32 v48, 1.0, v48
	v_add_f32_e32 v49, 1.0, v49
	v_add_f32_e32 v50, 1.0, v50
	v_add_f32_e32 v51, 1.0, v51
	v_min_f32_e32 v52, 0x7149f2ca, v52
	v_min_f32_e32 v53, 0x7149f2ca, v53
	v_min_f32_e32 v54, 0x7149f2ca, v54
	v_min_f32_e32 v55, 0x7149f2ca, v55
	v_min_f32_e32 v48, 0x7149f2ca, v48
	v_min_f32_e32 v49, 0x7149f2ca, v49
	v_min_f32_e32 v50, 0x7149f2ca, v50
	v_min_f32_e32 v51, 0x7149f2ca, v51
	v_cvt_pk_bf16_f32 v52, v52, v53
	v_cvt_pk_bf16_f32 v53, v54, v55
	v_cvt_pk_bf16_f32 v54, v48, v49
	v_cvt_pk_bf16_f32 v55, v50, v51
	v_mul_f32_e32 v102, 0xbfb8aa3b, v102
	v_mul_f32_e32 v103, 0xbfb8aa3b, v103
	v_mul_f32_e32 v104, 0xbfb8aa3b, v104
	v_mul_f32_e32 v105, 0xbfb8aa3b, v105
	v_mul_f32_e32 v98, 0xbfb8aa3b, v98
	v_mul_f32_e32 v99, 0xbfb8aa3b, v99
	v_mul_f32_e32 v100, 0xbfb8aa3b, v100
	v_mul_f32_e32 v101, 0xbfb8aa3b, v101
	v_exp_f32_e32 v102, v102
	v_exp_f32_e32 v103, v103
	v_exp_f32_e32 v104, v104
	v_exp_f32_e32 v105, v105
	v_exp_f32_e32 v98, v98
	v_exp_f32_e32 v99, v99
	v_exp_f32_e32 v100, v100
	v_exp_f32_e32 v101, v101
	v_add_f32_e32 v102, 1.0, v102
	v_add_f32_e32 v103, 1.0, v103
	v_add_f32_e32 v104, 1.0, v104
	v_add_f32_e32 v105, 1.0, v105
	v_add_f32_e32 v98, 1.0, v98
	v_add_f32_e32 v99, 1.0, v99
	v_add_f32_e32 v100, 1.0, v100
	v_add_f32_e32 v101, 1.0, v101
	v_min_f32_e32 v102, 0x7149f2ca, v102
	v_min_f32_e32 v103, 0x7149f2ca, v103
	v_min_f32_e32 v104, 0x7149f2ca, v104
	v_min_f32_e32 v105, 0x7149f2ca, v105
	v_min_f32_e32 v98, 0x7149f2ca, v98
	v_min_f32_e32 v99, 0x7149f2ca, v99
	v_min_f32_e32 v100, 0x7149f2ca, v100
	v_min_f32_e32 v101, 0x7149f2ca, v101
	v_cvt_pk_bf16_f32 v102, v102, v103
	v_cvt_pk_bf16_f32 v103, v104, v105
	v_cvt_pk_bf16_f32 v104, v98, v99
	v_cvt_pk_bf16_f32 v105, v100, v101
	v_mul_f32_e32 v44, 0xbfb8aa3b, v44
	v_mul_f32_e32 v45, 0xbfb8aa3b, v45
	v_mul_f32_e32 v46, 0xbfb8aa3b, v46
	v_mul_f32_e32 v47, 0xbfb8aa3b, v47
	v_mul_f32_e32 v40, 0xbfb8aa3b, v40
	v_mul_f32_e32 v41, 0xbfb8aa3b, v41
	v_mul_f32_e32 v42, 0xbfb8aa3b, v42
	v_mul_f32_e32 v43, 0xbfb8aa3b, v43
	v_exp_f32_e32 v44, v44
	v_exp_f32_e32 v45, v45
	v_exp_f32_e32 v46, v46
	v_exp_f32_e32 v47, v47
	v_exp_f32_e32 v40, v40
	v_exp_f32_e32 v41, v41
	v_exp_f32_e32 v42, v42
	v_exp_f32_e32 v43, v43
	v_add_f32_e32 v44, 1.0, v44
	v_add_f32_e32 v45, 1.0, v45
	v_add_f32_e32 v46, 1.0, v46
	v_add_f32_e32 v47, 1.0, v47
	v_add_f32_e32 v40, 1.0, v40
	v_add_f32_e32 v41, 1.0, v41
	v_add_f32_e32 v42, 1.0, v42
	v_add_f32_e32 v43, 1.0, v43
	v_min_f32_e32 v44, 0x7149f2ca, v44
	v_min_f32_e32 v45, 0x7149f2ca, v45
	v_min_f32_e32 v46, 0x7149f2ca, v46
	v_min_f32_e32 v47, 0x7149f2ca, v47
	v_min_f32_e32 v40, 0x7149f2ca, v40
	v_min_f32_e32 v41, 0x7149f2ca, v41
	v_min_f32_e32 v42, 0x7149f2ca, v42
	v_min_f32_e32 v43, 0x7149f2ca, v43
	v_cvt_pk_bf16_f32 v44, v44, v45
	v_cvt_pk_bf16_f32 v45, v46, v47
	v_cvt_pk_bf16_f32 v46, v40, v41
	v_cvt_pk_bf16_f32 v47, v42, v43
	v_mul_f32_e32 v92, 0xbfb8aa3b, v92
	v_mul_f32_e32 v93, 0xbfb8aa3b, v93
	v_mul_f32_e32 v94, 0xbfb8aa3b, v94
	v_mul_f32_e32 v95, 0xbfb8aa3b, v95
	v_mul_f32_e32 v88, 0xbfb8aa3b, v88
	v_mul_f32_e32 v89, 0xbfb8aa3b, v89
	v_mul_f32_e32 v90, 0xbfb8aa3b, v90
	v_mul_f32_e32 v91, 0xbfb8aa3b, v91
	v_exp_f32_e32 v92, v92
	v_exp_f32_e32 v93, v93
	v_exp_f32_e32 v94, v94
	v_exp_f32_e32 v95, v95
	v_exp_f32_e32 v88, v88
	v_exp_f32_e32 v89, v89
	v_exp_f32_e32 v90, v90
	v_exp_f32_e32 v91, v91
	v_add_f32_e32 v92, 1.0, v92
	v_add_f32_e32 v93, 1.0, v93
	v_add_f32_e32 v94, 1.0, v94
	v_add_f32_e32 v95, 1.0, v95
	v_add_f32_e32 v88, 1.0, v88
	v_add_f32_e32 v89, 1.0, v89
	v_add_f32_e32 v90, 1.0, v90
	v_add_f32_e32 v91, 1.0, v91
	v_min_f32_e32 v92, 0x7149f2ca, v92
	v_min_f32_e32 v93, 0x7149f2ca, v93
	v_min_f32_e32 v94, 0x7149f2ca, v94
	v_min_f32_e32 v95, 0x7149f2ca, v95
	v_min_f32_e32 v88, 0x7149f2ca, v88
	v_min_f32_e32 v89, 0x7149f2ca, v89
	v_min_f32_e32 v90, 0x7149f2ca, v90
	v_min_f32_e32 v91, 0x7149f2ca, v91
	v_cvt_pk_bf16_f32 v92, v92, v93
	v_cvt_pk_bf16_f32 v93, v94, v95
; __device__ __forceinline__ float sigm(float v) { return __builtin_amdgcn_rcpf(1.0f + __builtin_amdgcn_exp2f(-LOG2E * v)); }
; __device__ __forceinline__ unsigned cvt_pk_bf16(float lo, float hi) { f32x2_t v = {lo, hi}; bf16x2_t b = __builtin_convertvector(v, bf16x2_t); return __builtin_bit_cast(unsigned, b); }
; #define EPI_FENCE() asm volatile("" ::: "memory")
; #define EPI_LANE() int t__ = threadIdx.x; asm volatile("" : "+v"(t__)); const int wid__ = __builtin_amdgcn_readfirstlane(t__ >> 6); wr = wid__ >> 2; wc = wid__ & 3; fr = t__ & 15; fq = (t__ & 63) >> 4
; template <int MODE> __device__ __forceinline__ float actf(float v) {
;     if (MODE == 1) return v * sigm(v);
;     if (MODE == 2) return fminf(1.0f + __builtin_amdgcn_exp2f(-LOG2E * v), 1e30f);
;     if (MODE == 3) return v * QSCALE;
;     return v;
; }
;     template <int MODE> __device__ __forceinline__ void run(const f32x4 (&acc)[2][2][4][2], const Unit& u, int wr, int wc, int fr, int fq) const {
;         EPI_LANE();
;         const int pn = u.pn, colt = pn * BM, t = colt >> 9;
;         char* base = (MODE == 2) ? (char*)(O + (size_t)6 * ((size_t)MTOK * 512)) + ((size_t)(((pn - 12) * 128 + u.pm) * 8 + wid__)) * 16384
;                                  : (char*)(O + (size_t)t * ((size_t)MTOK * 512) + (size_t)u.pm * BM * 512 + (colt & 511));
;         unsigned off0 = (MODE == 2) ? (unsigned)((t__ & 63) * 16) : (unsigned)((wr * 64 + fr) * 512 + wc * 32 + 8 * fq) * 2u; asm volatile("" : "+v"(off0));
; #pragma unroll
;         for (int bj = 0; bj < 2; ++bj) {
; #pragma unroll
;             for (int ai = 0; ai < 2; ++ai)
; #pragma unroll
;                 for (int m = 0; m < 4; ++m) { const unsigned off = off0 + ((MODE == 2) ? (unsigned)(((ai * 4 + m) * 2 + bj) * 1024) : (unsigned)((ai * HALF + m * 16) * 512 + bj * HALF) * 2u);
;                     const f32x4 v0 = acc[ai][bj][m][0], v1 = acc[ai][bj][m][1];
;                     u32x4 w; w.x = cvt_pk_bf16(actf<MODE>(v0[0]), actf<MODE>(v0[1])); w.y = cvt_pk_bf16(actf<MODE>(v0[2]), actf<MODE>(v0[3]));
;                     w.z = cvt_pk_bf16(actf<MODE>(v1[0]), actf<MODE>(v1[1])); w.w = cvt_pk_bf16(actf<MODE>(v1[2]), actf<MODE>(v1[3]));
;                     *(u32x4*)(base + off) = w; }
;             EPI_FENCE();
;         }
	v_cvt_pk_bf16_f32 v94, v88, v89
	v_cvt_pk_bf16_f32 v95, v90, v91
	v_mul_f32_e32 v36, 0xbfb8aa3b, v36
	v_mul_f32_e32 v37, 0xbfb8aa3b, v37
	v_mul_f32_e32 v38, 0xbfb8aa3b, v38
	v_mul_f32_e32 v39, 0xbfb8aa3b, v39
	v_mul_f32_e32 v32, 0xbfb8aa3b, v32
	v_mul_f32_e32 v33, 0xbfb8aa3b, v33
	v_mul_f32_e32 v34, 0xbfb8aa3b, v34
	v_mul_f32_e32 v35, 0xbfb8aa3b, v35
	v_exp_f32_e32 v36, v36
	v_exp_f32_e32 v37, v37
	v_exp_f32_e32 v38, v38
	v_exp_f32_e32 v39, v39
	v_exp_f32_e32 v32, v32
	v_exp_f32_e32 v33, v33
	v_exp_f32_e32 v34, v34
	v_exp_f32_e32 v35, v35
	v_add_f32_e32 v36, 1.0, v36
	v_add_f32_e32 v37, 1.0, v37
	v_add_f32_e32 v38, 1.0, v38
	v_add_f32_e32 v39, 1.0, v39
	v_add_f32_e32 v32, 1.0, v32
	v_add_f32_e32 v33, 1.0, v33
	v_add_f32_e32 v34, 1.0, v34
	v_add_f32_e32 v35, 1.0, v35
	v_min_f32_e32 v36, 0x7149f2ca, v36
	v_min_f32_e32 v37, 0x7149f2ca, v37
	v_min_f32_e32 v38, 0x7149f2ca, v38
	v_min_f32_e32 v39, 0x7149f2ca, v39
	v_min_f32_e32 v32, 0x7149f2ca, v32
	v_min_f32_e32 v33, 0x7149f2ca, v33
	v_min_f32_e32 v34, 0x7149f2ca, v34
	v_min_f32_e32 v35, 0x7149f2ca, v35
	v_cvt_pk_bf16_f32 v36, v36, v37
	v_cvt_pk_bf16_f32 v37, v38, v39
	v_cvt_pk_bf16_f32 v38, v32, v33
	v_cvt_pk_bf16_f32 v39, v34, v35
	v_mul_f32_e32 v84, 0xbfb8aa3b, v84
	v_mul_f32_e32 v85, 0xbfb8aa3b, v85
	v_mul_f32_e32 v86, 0xbfb8aa3b, v86
	v_mul_f32_e32 v87, 0xbfb8aa3b, v87
	v_mul_f32_e32 v80, 0xbfb8aa3b, v80
	v_mul_f32_e32 v81, 0xbfb8aa3b, v81
	v_mul_f32_e32 v82, 0xbfb8aa3b, v82
	v_mul_f32_e32 v83, 0xbfb8aa3b, v83
	v_exp_f32_e32 v84, v84
	v_exp_f32_e32 v85, v85
	v_exp_f32_e32 v86, v86
	v_exp_f32_e32 v87, v87
	v_exp_f32_e32 v80, v80
	v_exp_f32_e32 v81, v81
	v_exp_f32_e32 v82, v82
	v_exp_f32_e32 v83, v83
	v_add_f32_e32 v84, 1.0, v84
	v_add_f32_e32 v85, 1.0, v85
	v_add_f32_e32 v86, 1.0, v86
	v_add_f32_e32 v87, 1.0, v87
	v_add_f32_e32 v80, 1.0, v80
	v_add_f32_e32 v81, 1.0, v81
	v_add_f32_e32 v82, 1.0, v82
	v_add_f32_e32 v83, 1.0, v83
	v_min_f32_e32 v84, 0x7149f2ca, v84
	v_min_f32_e32 v85, 0x7149f2ca, v85
	v_min_f32_e32 v86, 0x7149f2ca, v86
	v_min_f32_e32 v87, 0x7149f2ca, v87
	v_min_f32_e32 v80, 0x7149f2ca, v80
	v_min_f32_e32 v81, 0x7149f2ca, v81
	v_min_f32_e32 v82, 0x7149f2ca, v82
	v_min_f32_e32 v83, 0x7149f2ca, v83
	v_cvt_pk_bf16_f32 v84, v84, v85
	v_cvt_pk_bf16_f32 v85, v86, v87
	v_cvt_pk_bf16_f32 v86, v80, v81
	v_cvt_pk_bf16_f32 v87, v82, v83
	v_mul_f32_e32 v28, 0xbfb8aa3b, v28
	v_mul_f32_e32 v29, 0xbfb8aa3b, v29
	v_mul_f32_e32 v30, 0xbfb8aa3b, v30
	v_mul_f32_e32 v31, 0xbfb8aa3b, v31
	v_mul_f32_e32 v24, 0xbfb8aa3b, v24
	v_mul_f32_e32 v25, 0xbfb8aa3b, v25
	v_mul_f32_e32 v26, 0xbfb8aa3b, v26
	v_mul_f32_e32 v27, 0xbfb8aa3b, v27
	v_exp_f32_e32 v28, v28
	v_exp_f32_e32 v29, v29
	v_exp_f32_e32 v30, v30
	v_exp_f32_e32 v31, v31
	v_exp_f32_e32 v24, v24
	v_exp_f32_e32 v25, v25
	v_exp_f32_e32 v26, v26
	v_exp_f32_e32 v27, v27
	v_add_f32_e32 v28, 1.0, v28
	v_add_f32_e32 v29, 1.0, v29
	v_add_f32_e32 v30, 1.0, v30
	v_add_f32_e32 v31, 1.0, v31
	v_add_f32_e32 v24, 1.0, v24
	v_add_f32_e32 v25, 1.0, v25
	v_add_f32_e32 v26, 1.0, v26
	v_add_f32_e32 v27, 1.0, v27
	v_min_f32_e32 v28, 0x7149f2ca, v28
	v_min_f32_e32 v29, 0x7149f2ca, v29
	v_min_f32_e32 v30, 0x7149f2ca, v30
	v_min_f32_e32 v31, 0x7149f2ca, v31
	v_min_f32_e32 v24, 0x7149f2ca, v24
	v_min_f32_e32 v25, 0x7149f2ca, v25
	v_min_f32_e32 v26, 0x7149f2ca, v26
	v_min_f32_e32 v27, 0x7149f2ca, v27
	v_cvt_pk_bf16_f32 v28, v28, v29
	v_cvt_pk_bf16_f32 v29, v30, v31
	v_cvt_pk_bf16_f32 v30, v24, v25
	v_cvt_pk_bf16_f32 v31, v26, v27
	v_mul_f32_e32 v76, 0xbfb8aa3b, v76
	v_mul_f32_e32 v77, 0xbfb8aa3b, v77
	v_mul_f32_e32 v78, 0xbfb8aa3b, v78
	v_mul_f32_e32 v79, 0xbfb8aa3b, v79
	v_mul_f32_e32 v72, 0xbfb8aa3b, v72
	v_mul_f32_e32 v73, 0xbfb8aa3b, v73
	v_mul_f32_e32 v74, 0xbfb8aa3b, v74
	v_mul_f32_e32 v75, 0xbfb8aa3b, v75
	v_exp_f32_e32 v76, v76
	v_exp_f32_e32 v77, v77
	v_exp_f32_e32 v78, v78
	v_exp_f32_e32 v79, v79
	v_exp_f32_e32 v72, v72
	v_exp_f32_e32 v73, v73
	v_exp_f32_e32 v74, v74
	v_exp_f32_e32 v75, v75
	v_add_f32_e32 v76, 1.0, v76
	v_add_f32_e32 v77, 1.0, v77
	v_add_f32_e32 v78, 1.0, v78
	v_add_f32_e32 v79, 1.0, v79
	v_add_f32_e32 v72, 1.0, v72
	v_add_f32_e32 v73, 1.0, v73
	v_add_f32_e32 v74, 1.0, v74
	v_add_f32_e32 v75, 1.0, v75
	v_min_f32_e32 v76, 0x7149f2ca, v76
	v_min_f32_e32 v77, 0x7149f2ca, v77
	v_min_f32_e32 v78, 0x7149f2ca, v78
	v_min_f32_e32 v79, 0x7149f2ca, v79
	v_min_f32_e32 v72, 0x7149f2ca, v72
	v_min_f32_e32 v73, 0x7149f2ca, v73
	v_min_f32_e32 v74, 0x7149f2ca, v74
	v_min_f32_e32 v75, 0x7149f2ca, v75
	v_cvt_pk_bf16_f32 v76, v76, v77
	v_cvt_pk_bf16_f32 v77, v78, v79
	v_cvt_pk_bf16_f32 v78, v72, v73
	v_cvt_pk_bf16_f32 v79, v74, v75
	v_mul_f32_e32 v20, 0xbfb8aa3b, v20
	v_mul_f32_e32 v21, 0xbfb8aa3b, v21
	v_mul_f32_e32 v22, 0xbfb8aa3b, v22
	v_mul_f32_e32 v23, 0xbfb8aa3b, v23
	v_mul_f32_e32 v16, 0xbfb8aa3b, v16
; __device__ __forceinline__ float sigm(float v) { return __builtin_amdgcn_rcpf(1.0f + __builtin_amdgcn_exp2f(-LOG2E * v)); }
; __device__ __forceinline__ unsigned cvt_pk_bf16(float lo, float hi) { f32x2_t v = {lo, hi}; bf16x2_t b = __builtin_convertvector(v, bf16x2_t); return __builtin_bit_cast(unsigned, b); }
; #define EPI_FENCE() asm volatile("" ::: "memory")
; #define EPI_LANE() int t__ = threadIdx.x; asm volatile("" : "+v"(t__)); const int wid__ = __builtin_amdgcn_readfirstlane(t__ >> 6); wr = wid__ >> 2; wc = wid__ & 3; fr = t__ & 15; fq = (t__ & 63) >> 4
; template <int MODE> __device__ __forceinline__ float actf(float v) {
;     if (MODE == 1) return v * sigm(v);
;     if (MODE == 2) return fminf(1.0f + __builtin_amdgcn_exp2f(-LOG2E * v), 1e30f);
;     if (MODE == 3) return v * QSCALE;
;     return v;
; }
;     template <int MODE> __device__ __forceinline__ void run(const f32x4 (&acc)[2][2][4][2], const Unit& u, int wr, int wc, int fr, int fq) const {
;         EPI_LANE();
;         const int pn = u.pn, colt = pn * BM, t = colt >> 9;
;         char* base = (MODE == 2) ? (char*)(O + (size_t)6 * ((size_t)MTOK * 512)) + ((size_t)(((pn - 12) * 128 + u.pm) * 8 + wid__)) * 16384
;                                  : (char*)(O + (size_t)t * ((size_t)MTOK * 512) + (size_t)u.pm * BM * 512 + (colt & 511));
;         unsigned off0 = (MODE == 2) ? (unsigned)((t__ & 63) * 16) : (unsigned)((wr * 64 + fr) * 512 + wc * 32 + 8 * fq) * 2u; asm volatile("" : "+v"(off0));
; #pragma unroll
;         for (int bj = 0; bj < 2; ++bj) {
; #pragma unroll
;             for (int ai = 0; ai < 2; ++ai)
; #pragma unroll
;                 for (int m = 0; m < 4; ++m) { const unsigned off = off0 + ((MODE == 2) ? (unsigned)(((ai * 4 + m) * 2 + bj) * 1024) : (unsigned)((ai * HALF + m * 16) * 512 + bj * HALF) * 2u);
;                     const f32x4 v0 = acc[ai][bj][m][0], v1 = acc[ai][bj][m][1];
;                     u32x4 w; w.x = cvt_pk_bf16(actf<MODE>(v0[0]), actf<MODE>(v0[1])); w.y = cvt_pk_bf16(actf<MODE>(v0[2]), actf<MODE>(v0[3]));
;                     w.z = cvt_pk_bf16(actf<MODE>(v1[0]), actf<MODE>(v1[1])); w.w = cvt_pk_bf16(actf<MODE>(v1[2]), actf<MODE>(v1[3]));
;                     *(u32x4*)(base + off) = w; }
;             EPI_FENCE();
;         }
	v_mul_f32_e32 v17, 0xbfb8aa3b, v17
	v_mul_f32_e32 v18, 0xbfb8aa3b, v18
	v_mul_f32_e32 v19, 0xbfb8aa3b, v19
	v_exp_f32_e32 v20, v20
	v_exp_f32_e32 v21, v21
	v_exp_f32_e32 v22, v22
	v_exp_f32_e32 v23, v23
	v_exp_f32_e32 v16, v16
	v_exp_f32_e32 v17, v17
	v_exp_f32_e32 v18, v18
	v_exp_f32_e32 v19, v19
	v_add_f32_e32 v20, 1.0, v20
	v_add_f32_e32 v21, 1.0, v21
	v_add_f32_e32 v22, 1.0, v22
	v_add_f32_e32 v23, 1.0, v23
	v_add_f32_e32 v16, 1.0, v16
	v_add_f32_e32 v17, 1.0, v17
	v_add_f32_e32 v18, 1.0, v18
	v_add_f32_e32 v19, 1.0, v19
	v_min_f32_e32 v20, 0x7149f2ca, v20
	v_min_f32_e32 v21, 0x7149f2ca, v21
	v_min_f32_e32 v22, 0x7149f2ca, v22
	v_min_f32_e32 v23, 0x7149f2ca, v23
	v_min_f32_e32 v16, 0x7149f2ca, v16
	v_min_f32_e32 v17, 0x7149f2ca, v17
	v_min_f32_e32 v18, 0x7149f2ca, v18
	v_min_f32_e32 v19, 0x7149f2ca, v19
	v_cvt_pk_bf16_f32 v20, v20, v21
	v_cvt_pk_bf16_f32 v21, v22, v23
	v_cvt_pk_bf16_f32 v22, v16, v17
	v_cvt_pk_bf16_f32 v23, v18, v19
	v_mul_f32_e32 v12, 0xbfb8aa3b, v12
	v_mul_f32_e32 v13, 0xbfb8aa3b, v13
	v_mul_f32_e32 v14, 0xbfb8aa3b, v14
	v_mul_f32_e32 v15, 0xbfb8aa3b, v15
	v_mul_f32_e32 v8, 0xbfb8aa3b, v8
	v_mul_f32_e32 v9, 0xbfb8aa3b, v9
	v_mul_f32_e32 v10, 0xbfb8aa3b, v10
	v_mul_f32_e32 v11, 0xbfb8aa3b, v11
	v_exp_f32_e32 v12, v12
	v_exp_f32_e32 v13, v13
	v_exp_f32_e32 v14, v14
	v_exp_f32_e32 v15, v15
	v_exp_f32_e32 v8, v8
	v_exp_f32_e32 v9, v9
	v_exp_f32_e32 v10, v10
	v_exp_f32_e32 v11, v11
	v_add_f32_e32 v12, 1.0, v12
	v_add_f32_e32 v13, 1.0, v13
	v_add_f32_e32 v14, 1.0, v14
	v_add_f32_e32 v15, 1.0, v15
	v_add_f32_e32 v8, 1.0, v8
	v_add_f32_e32 v9, 1.0, v9
	v_add_f32_e32 v10, 1.0, v10
	v_add_f32_e32 v11, 1.0, v11
	v_min_f32_e32 v12, 0x7149f2ca, v12
	v_min_f32_e32 v13, 0x7149f2ca, v13
	v_min_f32_e32 v14, 0x7149f2ca, v14
	v_min_f32_e32 v15, 0x7149f2ca, v15
	v_min_f32_e32 v8, 0x7149f2ca, v8
	v_min_f32_e32 v9, 0x7149f2ca, v9
	v_min_f32_e32 v10, 0x7149f2ca, v10
	v_min_f32_e32 v11, 0x7149f2ca, v11
	v_cvt_pk_bf16_f32 v12, v12, v13
	v_cvt_pk_bf16_f32 v13, v14, v15
	v_cvt_pk_bf16_f32 v14, v8, v9
	v_cvt_pk_bf16_f32 v15, v10, v11
	v_mul_f32_e32 v4, 0xbfb8aa3b, v4
	v_mul_f32_e32 v5, 0xbfb8aa3b, v5
	v_mul_f32_e32 v6, 0xbfb8aa3b, v6
	v_mul_f32_e32 v7, 0xbfb8aa3b, v7
	v_mul_f32_e32 v0, 0xbfb8aa3b, v0
	v_mul_f32_e32 v1, 0xbfb8aa3b, v1
	v_mul_f32_e32 v2, 0xbfb8aa3b, v2
	v_mul_f32_e32 v3, 0xbfb8aa3b, v3
	v_exp_f32_e32 v4, v4
	v_exp_f32_e32 v5, v5
	v_exp_f32_e32 v6, v6
	v_exp_f32_e32 v7, v7
	v_exp_f32_e32 v0, v0
	v_exp_f32_e32 v1, v1
	v_exp_f32_e32 v2, v2
	v_exp_f32_e32 v3, v3
	v_add_f32_e32 v4, 1.0, v4
	v_add_f32_e32 v5, 1.0, v5
	v_add_f32_e32 v6, 1.0, v6
	v_add_f32_e32 v7, 1.0, v7
	v_add_f32_e32 v0, 1.0, v0
	v_add_f32_e32 v1, 1.0, v1
	v_add_f32_e32 v2, 1.0, v2
	v_add_f32_e32 v3, 1.0, v3
	v_min_f32_e32 v4, 0x7149f2ca, v4
	v_min_f32_e32 v5, 0x7149f2ca, v5
	v_min_f32_e32 v6, 0x7149f2ca, v6
	v_min_f32_e32 v7, 0x7149f2ca, v7
	v_min_f32_e32 v0, 0x7149f2ca, v0
	v_min_f32_e32 v1, 0x7149f2ca, v1
	v_min_f32_e32 v2, 0x7149f2ca, v2
	v_min_f32_e32 v3, 0x7149f2ca, v3
	v_cvt_pk_bf16_f32 v4, v4, v5
	v_cvt_pk_bf16_f32 v5, v6, v7
	v_cvt_pk_bf16_f32 v6, v0, v1
	v_cvt_pk_bf16_f32 v7, v2, v3
	s_mov_b32 exec_lo, 0x0f0f0f0f
	s_mov_b32 exec_hi, 0x0f0f0f0f
	global_store_dwordx4 v142, v[126:129], s[54:55]
	global_store_dwordx4 v144, v[68:71], s[54:55]
	global_store_dwordx4 v145, v[118:121], s[54:55]
	global_store_dwordx4 v146, v[60:63], s[54:55]
	global_store_dwordx4 v147, v[110:113], s[54:55]
	global_store_dwordx4 v148, v[52:55], s[54:55]
	global_store_dwordx4 v149, v[102:105], s[54:55]
	global_store_dwordx4 v150, v[44:47], s[54:55]
	global_store_dwordx4 v151, v[92:95], s[54:55]
	global_store_dwordx4 v152, v[36:39], s[54:55]
	global_store_dwordx4 v153, v[84:87], s[54:55]
	global_store_dwordx4 v154, v[28:31], s[54:55]
	global_store_dwordx4 v155, v[76:79], s[54:55]
	global_store_dwordx4 v156, v[20:23], s[54:55]
	global_store_dwordx4 v157, v[12:15], s[54:55]
	global_store_dwordx4 v158, v[4:7], s[54:55]
	s_not_b64 exec, exec
	global_store_dwordx4 v142, v[126:129], s[54:55]
	global_store_dwordx4 v144, v[68:71], s[54:55]
	global_store_dwordx4 v145, v[118:121], s[54:55]
	global_store_dwordx4 v146, v[60:63], s[54:55]
	global_store_dwordx4 v147, v[110:113], s[54:55]
	global_store_dwordx4 v148, v[52:55], s[54:55]
	global_store_dwordx4 v149, v[102:105], s[54:55]
	global_store_dwordx4 v150, v[44:47], s[54:55]
	global_store_dwordx4 v151, v[92:95], s[54:55]
	global_store_dwordx4 v152, v[36:39], s[54:55]
	global_store_dwordx4 v153, v[84:87], s[54:55]
	global_store_dwordx4 v154, v[28:31], s[54:55]
	global_store_dwordx4 v155, v[76:79], s[54:55]
	global_store_dwordx4 v156, v[20:23], s[54:55]
	global_store_dwordx4 v157, v[12:15], s[54:55]
	global_store_dwordx4 v158, v[4:7], s[54:55]
	s_mov_b64 exec, -1
